# scan y pass: waves 4-7 start ~384 cycles later (s_sleep 6) so the two waves of a SIMD are out of phase (stagger), on top of the C/B L2 prefetch
# speedup vs baseline: 1.0092x; 1.0008x over previous
; #define LAS __attribute__((address_space(3)))
; __device__ __forceinline__ unsigned cvt_pk_bf16(float lo, float hi) { const f32x2 v = {lo, hi}; return __builtin_bit_cast(unsigned, __builtin_convertvector(v, bf16x2_t)); }
; __device__ __forceinline__ u32x4 pack8(const float (&f)[8]) { u32x4 w; w.x = cvt_pk_bf16(f[0], f[1]); w.y = cvt_pk_bf16(f[2], f[3]); w.z = cvt_pk_bf16(f[4], f[5]); w.w = cvt_pk_bf16(f[6], f[7]); return w; }
; template <int MODE> __device__ __forceinline__ void ssd_scan_phase(Frame& F, int j, bool ctx_out) {
;     ...
;             bf16x8 xs2[2][4];
; #pragma unroll
;             for (int ks = 0; ks < 4; ++ks) { const f32x4 fa = *(const LAS f32x4*)(tab + 384 + 32 * ks + 8 * fq), fb = *(const LAS f32x4*)(tab + 384 + 32 * ks + 8 * fq + 4);
; #pragma unroll
;                 for (int pt = 0; pt < 2; ++pt) { float xv[8]; unpack8(__builtin_bit_cast(u32x4, xf[pt][ks]), xv);
;                     xv[0] *= fa.x; xv[1] *= fa.y; xv[2] *= fa.z; xv[3] *= fa.w; xv[4] *= fb.x; xv[5] *= fb.y; xv[6] *= fb.z; xv[7] *= fb.w;
;                     xs2[pt][ks] = __builtin_bit_cast(bf16x8, pack8(xv)); } }
;             if (need_y && !(MODE & 2)) {
;                 bf16x8 cf[4];
; #pragma unroll
;                 for (int ks = 0; ks < 4; ++ks) cf[ks] = *(const LAS bf16x8*)(CS + (16 * w + fr) * 256 + (((4 * ks + fq) ^ fr) << 4));
; #pragma unroll 2
;                 for (int st = 0; st < 8; ++st) { f32x4 acc = (f32x4){0.f, 0.f, 0.f, 0.f};
; #pragma unroll
;                     for (int ks = 0; ks < 4; ++ks) { const bf16x8 bfr = *(const LAS bf16x8*)(BS + (16 * st + fr) * 256 + (((4 * ks + fq) ^ fr) << 4)); acc = __builtin_amdgcn_mfma_f32_16x16x32_bf16(bfr, cf[ks], acc, 0, 0, 0); }
;                     u32x2 o; o.x = cvt_pk_bf16(acc[0], acc[1]); o.y = cvt_pk_bf16(acc[2], acc[3]);
;                     *(LAS u32x2*)(GS + (16 * w + fr) * 256 + (((2 * st + (fq >> 1)) ^ fr) << 4) + (fq & 1) * 8) = o; }
;             }
;             __syncthreads();
;             if (!(MODE & 8)) SCAN_DMA(BS, btp, T);
.LBB0_487:
	v_lshlrev_b32_e32 v92, 16, v140
	v_and_b32_e32 v93, 0xffff0000, v140
	v_lshlrev_b32_e32 v94, 16, v141
	v_and_b32_e32 v95, 0xffff0000, v141
	v_lshlrev_b32_e32 v120, 16, v142
	v_and_b32_e32 v121, 0xffff0000, v142
	s_waitcnt lgkmcnt(7)
	v_pk_mul_f32 v[92:93], v[96:97], v[92:93]
	v_pk_mul_f32 v[94:95], v[98:99], v[94:95]
	s_waitcnt lgkmcnt(6)
	v_pk_mul_f32 v[120:121], v[84:85], v[120:121]
	v_cvt_pk_bf16_f32 v92, v92, v93
	v_cvt_pk_bf16_f32 v93, v94, v95
	v_cvt_pk_bf16_f32 v94, v120, v121
	v_lshlrev_b32_e32 v120, 16, v144
	v_and_b32_e32 v121, 0xffff0000, v144
	v_pk_mul_f32 v[96:97], v[96:97], v[120:121]
	v_lshlrev_b32_e32 v120, 16, v145
	v_and_b32_e32 v121, 0xffff0000, v145
	v_pk_mul_f32 v[98:99], v[98:99], v[120:121]
	v_lshlrev_b32_e32 v120, 16, v146
	v_and_b32_e32 v121, 0xffff0000, v146
	v_lshlrev_b32_e32 v122, 16, v143
	v_and_b32_e32 v123, 0xffff0000, v143
	v_pk_mul_f32 v[84:85], v[84:85], v[120:121]
	v_lshlrev_b32_e32 v120, 16, v147
	v_and_b32_e32 v121, 0xffff0000, v147
	v_pk_mul_f32 v[122:123], v[86:87], v[122:123]
	v_pk_mul_f32 v[86:87], v[86:87], v[120:121]
	v_cvt_pk_bf16_f32 v96, v96, v97
	v_cvt_pk_bf16_f32 v97, v98, v99
	v_cvt_pk_bf16_f32 v98, v84, v85
	v_cvt_pk_bf16_f32 v99, v86, v87
	v_lshlrev_b32_e32 v84, 16, v136
	v_and_b32_e32 v85, 0xffff0000, v136
	v_lshlrev_b32_e32 v86, 16, v137
	v_and_b32_e32 v87, 0xffff0000, v137
	v_lshlrev_b32_e32 v120, 16, v138
	v_and_b32_e32 v121, 0xffff0000, v138
	s_waitcnt lgkmcnt(5)
	v_pk_mul_f32 v[84:85], v[88:89], v[84:85]
	v_pk_mul_f32 v[86:87], v[90:91], v[86:87]
	s_waitcnt lgkmcnt(4)
	v_pk_mul_f32 v[120:121], v[80:81], v[120:121]
	v_cvt_pk_bf16_f32 v84, v84, v85
	v_cvt_pk_bf16_f32 v85, v86, v87
	v_cvt_pk_bf16_f32 v86, v120, v121
	v_lshlrev_b32_e32 v120, 16, v76
	v_and_b32_e32 v121, 0xffff0000, v76
	v_lshlrev_b32_e32 v76, 16, v77
	v_and_b32_e32 v77, 0xffff0000, v77
	v_pk_mul_f32 v[76:77], v[90:91], v[76:77]
	v_lshlrev_b32_e32 v90, 16, v78
	v_and_b32_e32 v91, 0xffff0000, v78
	v_lshlrev_b32_e32 v78, 16, v79
	v_and_b32_e32 v79, 0xffff0000, v79
	v_pk_mul_f32 v[88:89], v[88:89], v[120:121]
	v_pk_mul_f32 v[80:81], v[80:81], v[90:91]
	v_pk_mul_f32 v[78:79], v[82:83], v[78:79]
	v_cvt_pk_bf16_f32 v95, v122, v123
	v_lshlrev_b32_e32 v122, 16, v139
	v_and_b32_e32 v123, 0xffff0000, v139
	v_cvt_pk_bf16_f32 v88, v88, v89
	v_cvt_pk_bf16_f32 v89, v76, v77
	v_cvt_pk_bf16_f32 v90, v80, v81
	v_cvt_pk_bf16_f32 v91, v78, v79
	v_lshlrev_b32_e32 v76, 16, v100
	v_and_b32_e32 v77, 0xffff0000, v100
	v_lshlrev_b32_e32 v78, 16, v101
	v_and_b32_e32 v79, 0xffff0000, v101
	v_lshlrev_b32_e32 v80, 16, v102
	v_and_b32_e32 v81, 0xffff0000, v102
	v_pk_mul_f32 v[122:123], v[82:83], v[122:123]
	s_waitcnt lgkmcnt(3)
	v_pk_mul_f32 v[76:77], v[116:117], v[76:77]
	v_pk_mul_f32 v[78:79], v[118:119], v[78:79]
	s_waitcnt lgkmcnt(2)
	v_pk_mul_f32 v[82:83], v[112:113], v[80:81]
	v_lshlrev_b32_e32 v80, 16, v103
	v_and_b32_e32 v81, 0xffff0000, v103
	v_pk_mul_f32 v[120:121], v[114:115], v[80:81]
	v_cvt_pk_bf16_f32 v80, v76, v77
	v_cvt_pk_bf16_f32 v81, v78, v79
	v_lshlrev_b32_e32 v76, 16, v48
	v_and_b32_e32 v77, 0xffff0000, v48
	v_lshlrev_b32_e32 v48, 16, v49
	v_and_b32_e32 v49, 0xffff0000, v49
	v_lshlrev_b32_e32 v78, 16, v50
	v_and_b32_e32 v79, 0xffff0000, v50
	v_lshlrev_b32_e32 v50, 16, v51
	v_and_b32_e32 v51, 0xffff0000, v51
	v_pk_mul_f32 v[76:77], v[116:117], v[76:77]
	v_pk_mul_f32 v[48:49], v[118:119], v[48:49]
	v_pk_mul_f32 v[78:79], v[112:113], v[78:79]
	v_pk_mul_f32 v[50:51], v[114:115], v[50:51]
	v_cvt_pk_bf16_f32 v76, v76, v77
	v_cvt_pk_bf16_f32 v77, v48, v49
	v_cvt_pk_bf16_f32 v78, v78, v79
	v_cvt_pk_bf16_f32 v79, v50, v51
	v_lshlrev_b32_e32 v48, 16, v8
	v_and_b32_e32 v49, 0xffff0000, v8
	v_lshlrev_b32_e32 v50, 16, v9
	v_and_b32_e32 v51, 0xffff0000, v9
	v_lshlrev_b32_e32 v112, 16, v10
	v_and_b32_e32 v113, 0xffff0000, v10
	s_waitcnt lgkmcnt(1)
	v_pk_mul_f32 v[48:49], v[108:109], v[48:49]
	v_pk_mul_f32 v[50:51], v[110:111], v[50:51]
	s_waitcnt lgkmcnt(0)
	v_pk_mul_f32 v[112:113], v[104:105], v[112:113]
	v_cvt_pk_bf16_f32 v48, v48, v49
	v_cvt_pk_bf16_f32 v49, v50, v51
	v_cvt_pk_bf16_f32 v50, v112, v113
	v_lshlrev_b32_e32 v112, 16, v44
	v_and_b32_e32 v113, 0xffff0000, v44
	v_lshlrev_b32_e32 v44, 16, v45
	v_and_b32_e32 v45, 0xffff0000, v45
	s_and_b64 s[46:47], exec, s[46:47]
	v_pk_mul_f32 v[110:111], v[110:111], v[44:45]
	v_lshlrev_b32_e32 v44, 16, v46
	v_and_b32_e32 v45, 0xffff0000, v46
	s_cselect_b32 s17, 1, 17
	v_lshlrev_b32_e32 v114, 16, v11
	v_and_b32_e32 v115, 0xffff0000, v11
	v_pk_mul_f32 v[104:105], v[104:105], v[44:45]
	v_lshlrev_b32_e32 v44, 16, v47
	v_and_b32_e32 v45, 0xffff0000, v47
	s_cselect_b32 s27, s4, s93
	s_sub_i32 s17, s17, s4
	v_pk_mul_f32 v[114:115], v[106:107], v[114:115]
	v_pk_mul_f32 v[106:107], v[106:107], v[44:45]
	s_and_b64 s[46:47], s[38:39], exec
	v_cvt_pk_bf16_f32 v47, v106, v107
	v_add_u32_e32 v106, s33, v209
	s_cselect_b32 s43, s27, s17
	v_ashrrev_i32_e32 v188, 4, v106
	s_lshl_b32 s17, s43, 8
	v_xor_b32_e32 v107, v188, v209
	s_add_u32 s46, s48, s17
	v_lshlrev_b32_e32 v107, 3, v107
	s_addc_u32 s47, s49, 0
	v_cvt_pk_bf16_f32 v46, v104, v105
	v_mad_i64_i32 v[104:105], s[48:49], s42, v188, 0
	v_and_b32_e32 v107, 0x78, v107
	v_lshl_add_u64 v[104:105], v[104:105], 1, s[46:47]
	v_lshlrev_b32_e32 v182, 1, v107
	v_mov_b32_e32 v183, v177
	s_add_i32 s17, s26, s3
	v_lshl_add_u64 v[104:105], v[104:105], 0, v[182:183]
	s_mov_b32 m0, s17
	s_barrier
; #define LAS __attribute__((address_space(3)))
; __device__ __forceinline__ unsigned cvt_pk_bf16(float lo, float hi) { const f32x2 v = {lo, hi}; return __builtin_bit_cast(unsigned, __builtin_convertvector(v, bf16x2_t)); }
; template <int MODE> __device__ __forceinline__ void ssd_scan_phase(Frame& F, int j, bool ctx_out) {
;     ...
;             if (!(MODE & 8)) SCAN_DMA(BS, btp, T);
;             if (need_y && !(MODE & 1)) {
;                 bf16x8 hf[2][4];
; #pragma unroll
;                 for (int pt = 0; pt < 2; ++pt)
; #pragma unroll
;                     for (int q = 0; q < 4; ++q) { const f32x4 lo4 = hT[2 * q][pt], hi4 = hT[2 * q + 1][pt]; u32x4 o; o.x = cvt_pk_bf16(lo4[0], lo4[1]); o.y = cvt_pk_bf16(lo4[2], lo4[3]); o.z = cvt_pk_bf16(hi4[0], hi4[1]); o.w = cvt_pk_bf16(hi4[2], hi4[3]);
;                         hf[pt][q] = __builtin_bit_cast(bf16x8, o); }
;                 bf16x8 xb_cur = xf[1][0], xb_nxt = xf[1][0];
; #pragma unroll 8
;                 for (int lt = 0; lt < 8; ++lt) {
;                     const int l = 16 * lt + fr; const float cl = tab[l];
;                     f32x4 accd[2], acco[2];
;                     accd[0] = accd[1] = acco[0] = acco[1] = (f32x4){0.f, 0.f, 0.f, 0.f};
;                     const int kd = lt >> 1;
;                     if ((lt & 1) == 0) { xb_cur = xb_nxt; if (kd + 1 < 4) xb_nxt = *(const bf16x8*)(xl + (size_t)16 * T + 32 * (kd + 1)); }
;                     const bf16x8 xa = xf[0][kd], xb = xb_cur;
; #pragma unroll
;                     for (int ks = 0; ks < 4; ++ks) {
;                         const bool full = dir == 0 ? (ks < kd) : (ks > kd);
;                         if (full) {
;                             const bf16x8 gf = *(const LAS bf16x8*)(GS + l * 256 + (((4 * ks + fq) ^ fr) << 4));
;                             const float f1 = __builtin_amdgcn_exp2f(cl - tab[dir == 0 ? 32 * ks + 31 : 32 * ks]);
;                             const f32x4 z4 = (f32x4){0.f, 0.f, 0.f, 0.f};
;                             const f32x4 t0 = __builtin_amdgcn_mfma_f32_16x16x32_bf16(xs2[0][ks], gf, z4, 0, 0, 0), t1 = __builtin_amdgcn_mfma_f32_16x16x32_bf16(xs2[1][ks], gf, z4, 0, 0, 0);
;                             accd[0] += t0 * f1; accd[1] += t1 * f1;
;                         }
	global_load_lds_dwordx4 v[104:105], off
	v_add_u32_e32 v104, 0x200, v106
	v_ashrrev_i32_e32 v192, 4, v104
	v_xor_b32_e32 v107, v192, v209
	v_lshlrev_b32_e32 v107, 3, v107
	v_mad_i64_i32 v[104:105], s[48:49], s42, v192, 0
	v_and_b32_e32 v107, 0x78, v107
	v_lshl_add_u64 v[104:105], v[104:105], 1, s[46:47]
	v_lshlrev_b32_e32 v184, 1, v107
	v_mov_b32_e32 v185, v177
	v_lshl_add_u64 v[104:105], v[104:105], 0, v[184:185]
	s_add_i32 m0, s17, 0x2000
	v_mov_b32_e32 v187, v177
	global_load_lds_dwordx4 v[104:105], off
	v_add_u32_e32 v104, 0x400, v106
	v_ashrrev_i32_e32 v194, 4, v104
	v_xor_b32_e32 v107, v194, v209
	v_lshlrev_b32_e32 v107, 3, v107
	v_mad_i64_i32 v[104:105], s[48:49], s42, v194, 0
	v_and_b32_e32 v107, 0x78, v107
	v_lshl_add_u64 v[104:105], v[104:105], 1, s[46:47]
	v_lshlrev_b32_e32 v186, 1, v107
	v_lshl_add_u64 v[104:105], v[104:105], 0, v[186:187]
	s_add_i32 m0, s17, 0x4000
	v_mov_b32_e32 v191, v177
	global_load_lds_dwordx4 v[104:105], off
	v_add_u32_e32 v104, 0x600, v106
	v_ashrrev_i32_e32 v196, 4, v104
	v_xor_b32_e32 v106, v196, v209
	v_lshlrev_b32_e32 v106, 3, v106
	v_mad_i64_i32 v[104:105], s[48:49], s42, v196, 0
	v_and_b32_e32 v106, 0x78, v106
	v_lshl_add_u64 v[104:105], v[104:105], 1, s[46:47]
	v_lshlrev_b32_e32 v190, 1, v106
	v_lshl_add_u64 v[104:105], v[104:105], 0, v[190:191]
	s_add_i32 m0, s17, 0x6000
	v_pk_mul_f32 v[108:109], v[108:109], v[112:113]
	global_load_lds_dwordx4 v[104:105], off
	v_cvt_pk_bf16_f32 v87, v122, v123
	v_cvt_pk_bf16_f32 v82, v82, v83
	v_cvt_pk_bf16_f32 v83, v120, v121
	v_cvt_pk_bf16_f32 v51, v114, v115
	v_cvt_pk_bf16_f32 v44, v108, v109
	v_cvt_pk_bf16_f32 v45, v110, v111
	s_andn2_b64 vcc, exec, s[40:41]
	s_cbranch_vccnz .LBB0_523
	s_lshl_b32 s40, s43, 7
	s_lshl_b32 s17, s40, 1
	v_mul_u32_u24_e32 v104, s42, v176
	s_add_u32 s44, s44, s17
	s_addc_u32 s45, s45, 0
	v_lshlrev_b32_e32 v104, 1, v104
	v_mov_b32_e32 v105, v177
	v_lshl_add_u64 v[104:105], s[44:45], 0, v[104:105]
	v_lshl_add_u64 v[104:105], v[180:181], 1, v[104:105]
	s_lshl_b32 s42, s42, 5
	s_mov_b32 s43, s92
	v_lshl_add_u64 v[200:201], v[104:105], 0, s[42:43]
	global_load_dwordx4 v[148:151], v[200:201], off offset:64
	s_cmp_lt_u32 s18, 0x1a000
	s_cbranch_scc1 .Lscan_stag_skip
	s_sleep 6
.Lscan_stag_skip:
	v_lshl_add_u32 v214, v176, 2, s18
	ds_read_b32 v216, v214
	v_cndmask_b32_e64 v104, 0, 1, s[36:37]
	v_cmp_ne_u32_e64 s[44:45], 1, v104
	s_andn2_b64 vcc, exec, s[36:37]
	v_add_u32_e32 v166, s87, v132
	s_cbranch_vccnz .LBB0_490
	v_mov_b32_e32 v108, s18
	v_lshl_add_u32 v104, v207, 4, v166
	ds_read_b32 v112, v108 offset:128
	ds_read_b128 v[104:107], v104
	s_waitcnt lgkmcnt(0)
	v_mfma_f32_16x16x32_bf16 v[108:111], v[84:87], v[104:107], 0
	v_sub_f32_e32 v112, v216, v112
	v_exp_f32_e32 v112, v112
	v_mfma_f32_16x16x32_bf16 v[104:107], v[88:91], v[104:107], 0
	s_nop 4
	v_fma_f32 v156, v108, v112, 0
	v_fma_f32 v157, v109, v112, 0
	v_pk_fma_f32 v[158:159], v[110:111], v[112:113], 0 op_sel_hi:[1,0,0]
	v_pk_fma_f32 v[152:153], v[104:105], v[112:113], 0 op_sel_hi:[1,0,0]
	v_pk_fma_f32 v[154:155], v[106:107], v[112:113], 0 op_sel_hi:[1,0,0]
	s_and_b64 vcc, exec, s[44:45]
	s_cbranch_vccz .LBB0_491
	s_branch .LBB0_492
